# retention scan phase (P2b) rewritten by hand: same algorithm/layout, single batched LDS reduction reads, counted vmcnt(9) prefetch waits, no per-step branching; plus P5 row-scale caching
# speedup vs baseline: 1.0202x; 1.0027x over previous
; #define LAS __attribute__((address_space(3)))
; #define LDS_WAIT() asm volatile("s_waitcnt lgkmcnt(0)" ::: "memory")
; __device__ __forceinline__ float head_lg2(int h) { return log2f(1.0f - exp2f(-5.0f - (float)h)); }
; #define SCAN_LOADV(VSET, CH) do { const size_t c_ = (size_t)(CH); \
;             _Pragma("unroll") for (int s = 0; s < 4; ++s) kf[VSET][s] = *(const bf16x8*)(kp + c_ * 32768 + 1024 * s + voff); } while (0)
; __device__ __forceinline__ void scan_phase(const bf16* q, const bf16* kdT, const bf16* vT, const bf16* Pp, bf16* o, LAS unsigned char* lds, int bid, int G, int wave, int lane, int tid) {
;     const int rnt = tid >> 8, rj = (tid >> 6) & 3, rhh = (tid >> 5) & 1, rv = tid & 31, rn0 = 32 * rnt + 8 * rj + 4 * rhh;
;     for (int unit = bid; unit < 256; unit += G) {
;         const int bh = (unit & 7) * 4 + (unit >> 6), vs = (unit >> 3) & 7, b = bh >> 3, h = bh & 7;
;         const float lg2 = head_lg2(h), cd = exp2f(64.0f * lg2);
;         float qd[4];
; #pragma unroll
;         for (int e = 0; e < 4; ++e) qd[e] = exp2f((float)(rn0 + e + 1) * lg2);
;         const char* kp = (const char*)kdT + ((size_t)bh * 64 * 16384 + wave * 2048) * 2;
;         const char* vp = (const char*)vT + ((size_t)bh * 64 * 16384 + vs * 2048) * 2;
;         const char* qp = (const char*)q + ((size_t)bh * 64 * 16384 + wave * 2048) * 2;
;         const char* pp = (const char*)Pp + ((size_t)bh * 64 * 4096 + wave * 512) * 2;
;         const unsigned voff = (unsigned)lane * 16u;
;         bf16* op = o + (size_t)(b * SEQ + rn0) * 2048 + h * 256 + 32 * vs + rv;
;         const int iks = wave & 3, int_ = wave >> 2;
;         const int rboff = ((rnt * 2 + (rj >> 1)) * 64 + rhh * 32 + rv) * 16 + (rj & 1) * 8;
;         f32x16 S;
; #pragma unroll
;         for (int e = 0; e < 16; ++e) S[e] = 0.f;
;         bf16x8 kf[2][4], vf[4], vst, qf[3][2][2], pf[3];
;     ...
;         SCAN_LOAD(0, 0); SCAN_LOAD(1, 1); SCAN_LOADV(0, 0);
;         vst = *(const bf16x8*)(vp + 1024 * (wave & 3) + voff);
;         if (wave < 4) { *(LAS bf16x8*)(lds + 65536 + wave * 1024 + voff) = vst; vst = *(const bf16x8*)(vp + (size_t)32768 + 1024 * wave + voff); }
;         LDS_WAIT(); __builtin_amdgcn_s_barrier(); asm volatile("" ::: "memory");
; #pragma unroll
;         for (int s = 0; s < 4; ++s) vf[s] = *(const LAS bf16x8*)(lds + 65536 + s * 1024 + voff);
.LBB0_431:
	s_or_b64 exec, exec, s[0:1]
	s_cmpk_lt_i32 s2, 0x100
	s_cselect_b64 s[10:11], -1, 0
	s_waitcnt vmcnt(31)
	v_mov_b32_e32 v2, v0
	s_waitcnt lgkmcnt(0)
	s_barrier
	s_mov_b64 s[12:13], s[30:31]
	v_readfirstlane_b32 s0, v2
	s_and_b64 vcc, exec, s[10:11]
	s_cbranch_vccz .LBB0_719
	s_lshr_b32 s4, s0, 6
	s_and_b32 s6, s4, 3
	s_lshr_b32 s7, s4, 2
	s_movk_i32 s23, 0x7fff
	s_cmp_lt_u32 s4, 4
	s_cselect_b64 s[34:35], -1, 0
	v_and_b32_e32 v1, 63, v0
	v_lshlrev_b32_e32 v1, 4, v1
	s_and_b32 s52, s2, 7
	s_lshl_b32 s52, s52, 2
	s_lshr_b32 s53, s2, 6
	s_add_i32 s52, s52, s53
	s_bfe_u32 s53, s2, 0x30003
	s_lshr_b32 s54, s52, 3
	s_and_b32 s55, s52, 7
	s_lshl_b32 s56, s52, 21
	s_lshl_b32 s57, s4, 12
	s_add_u32 s58, s56, s57
	s_add_u32 s8, s30, s58
	s_addc_u32 s9, s31, 0
	s_add_u32 s8, s8, 0x5800000
	s_addc_u32 s9, s9, 0
	s_add_u32 s14, s30, s58
	s_addc_u32 s15, s31, 0
	s_add_u32 s14, s14, 0x11800000
	s_addc_u32 s15, s15, 0
	s_lshl_b32 s59, s53, 12
	s_add_u32 s59, s59, s56
	s_lshl_b32 s60, s6, 10
	s_add_u32 s59, s59, s60
	s_add_u32 s16, s30, s59
	s_addc_u32 s17, s31, 0
	s_add_u32 s16, s16, 0xd800000
	s_addc_u32 s17, s17, 0
	s_lshl_b32 s59, s52, 19
	s_lshl_b32 s60, s4, 10
	s_add_u32 s59, s59, s60
	s_add_u32 s18, s30, s59
	s_addc_u32 s19, s31, 0
	s_add_u32 s18, s18, 0x19800000
	s_addc_u32 s19, s19, 0
	s_lshl_b32 s59, s54, 24
	s_lshl_b32 s60, s55, 9
	s_add_u32 s59, s59, s60
	s_lshl_b32 s60, s53, 6
	s_add_u32 s59, s59, s60
	s_add_u32 s20, s30, s59
	s_addc_u32 s21, s31, 0
	s_add_u32 s20, s20, 0x9800000
	s_addc_u32 s21, s21, 0
	global_load_dwordx4 v[118:121], v1, s[14:15]
	global_load_dwordx4 v[122:125], v1, s[14:15] offset:1024
	global_load_dwordx4 v[126:129], v1, s[14:15] offset:2048
	global_load_dwordx4 v[130:133], v1, s[14:15] offset:3072
	global_load_dwordx4 v[58:61], v1, s[8:9]
	global_load_dwordx4 v[62:65], v1, s[8:9] offset:1024
	global_load_dwordx4 v[66:69], v1, s[8:9] offset:2048
	global_load_dwordx4 v[70:73], v1, s[8:9] offset:3072
	global_load_dwordx4 v[74:77], v1, s[18:19]
	s_add_u32 s8, s8, 0x8000
	s_addc_u32 s9, s9, 0
	s_add_u32 s18, s18, 0x2000
	s_addc_u32 s19, s19, 0
	global_load_dwordx4 v[78:81], v1, s[8:9]
	global_load_dwordx4 v[82:85], v1, s[8:9] offset:1024
	global_load_dwordx4 v[86:89], v1, s[8:9] offset:2048
	global_load_dwordx4 v[90:93], v1, s[8:9] offset:3072
	global_load_dwordx4 v[94:97], v1, s[18:19]
	s_add_u32 s8, s8, 0x8000
	s_addc_u32 s9, s9, 0
	s_add_u32 s18, s18, 0x2000
	s_addc_u32 s19, s19, 0
	s_add_u32 s14, s14, 0x8000
	s_addc_u32 s15, s15, 0
	s_andn2_b64 vcc, exec, s[34:35]
	s_cbranch_vccnz .Lp2b_pv_1
	global_load_dwordx4 v[170:173], v1, s[16:17]
.Lp2b_pv_1:
	s_add_u32 s16, s16, 0x8000
	s_addc_u32 s17, s17, 0
	v_lshrrev_b32_e32 v178, 8, v0
	v_bfe_u32 v179, v0, 6, 2
	v_bfe_u32 v180, v0, 5, 1
	v_and_b32_e32 v181, 31, v0
	v_lshlrev_b32_e32 v182, 5, v178
	v_lshl_add_u32 v182, v179, 3, v182
	v_lshl_add_u32 v182, v180, 2, v182
	v_lshrrev_b32_e32 v183, 1, v179
	v_lshl_add_u32 v183, v178, 1, v183
	v_lshlrev_b32_e32 v183, 6, v183
	v_lshl_add_u32 v183, v180, 5, v183
	v_add_u32_e32 v183, v183, v181
	v_lshlrev_b32_e32 v183, 4, v183
	v_and_b32_e32 v184, 1, v179
	v_lshl_add_u32 v193, v184, 3, v183
	v_lshlrev_b32_e32 v183, 12, v182
	v_lshl_add_u32 v183, v181, 1, v183
	v_add_u32_e32 v197, 0x1000, v183
	v_add_u32_e32 v198, 0x3000, v183
	v_add_u32_e32 v192, s57, v1
	v_add_u32_e32 v195, 0x10000, v1
	s_lshl_b32 s59, s4, 10
	v_add_u32_e32 v194, s59, v195
	s_lshl_b32 s59, s6, 10
	v_add_u32_e32 v196, s59, v195
	v_cvt_f32_ubyte0_e32 v183, s55
	v_sub_f32_e32 v183, 0xc0a00000, v183
	v_exp_f32_e32 v183, v183
	s_nop 0
	v_sub_f32_e32 v183, 1.0, v183
	v_log_f32_e32 v183, v183
	v_or_b32_e32 v184, 1, v182
	v_cvt_f32_i32_e32 v184, v184
	v_mul_f32_e32 v184, v183, v184
	v_exp_f32_e32 v186, v184
	v_or_b32_e32 v184, 2, v182
	v_cvt_f32_i32_e32 v184, v184
	v_mul_f32_e32 v184, v183, v184
	v_exp_f32_e32 v187, v184
	v_or_b32_e32 v184, 3, v182
	v_cvt_f32_i32_e32 v184, v184
	v_mul_f32_e32 v184, v183, v184
	v_exp_f32_e32 v188, v184
	v_add_u32_e32 v184, 4, v182
	v_cvt_f32_i32_e32 v184, v184
	v_mul_f32_e32 v184, v183, v184
	v_exp_f32_e32 v189, v184
	v_mul_f32_e32 v184, 0x42800000, v183
	v_exp_f32_e32 v190, v184
	v_mov_b32_e32 v2, 0
	v_mov_b32_e32 v3, 0
	v_mov_b32_e32 v4, 0
	v_mov_b32_e32 v5, 0
	v_mov_b32_e32 v6, 0
	v_mov_b32_e32 v7, 0
	v_mov_b32_e32 v8, 0
	v_mov_b32_e32 v9, 0
	v_mov_b32_e32 v10, 0
	v_mov_b32_e32 v11, 0
	v_mov_b32_e32 v12, 0
	v_mov_b32_e32 v13, 0
	v_mov_b32_e32 v14, 0
	v_mov_b32_e32 v15, 0
	v_mov_b32_e32 v16, 0
	v_mov_b32_e32 v17, 0
	s_andn2_b64 vcc, exec, s[34:35]
	s_cbranch_vccnz .Lp2b_pv_2
	s_waitcnt vmcnt(0)
	ds_write_b128 v194, v[170:173]
	global_load_dwordx4 v[170:173], v1, s[16:17]
.Lp2b_pv_2:
	s_add_u32 s16, s16, 0x8000
	s_addc_u32 s17, s17, 0
	s_waitcnt lgkmcnt(0)
	s_barrier
	ds_read_b128 v[150:153], v195
	ds_read_b128 v[154:157], v195 offset:1024
	ds_read_b128 v[158:161], v195 offset:2048
	ds_read_b128 v[162:165], v195 offset:3072
	ds_read_b128 v[166:169], v196
	s_waitcnt vmcnt(0)
	s_mov_b32 s22, 0
.Lp2b_loop:
	s_waitcnt vmcnt(9)
	s_andn2_b64 vcc, exec, s[34:35]
	s_cbranch_vccnz .Lp2b_sv_3
	ds_write_b128 v194, v[170:173] offset:4096
	global_load_dwordx4 v[170:173], v1, s[16:17]
.Lp2b_sv_3:
	global_load_dwordx4 v[134:137], v1, s[14:15]
	global_load_dwordx4 v[138:141], v1, s[14:15] offset:1024
	global_load_dwordx4 v[142:145], v1, s[14:15] offset:2048
	global_load_dwordx4 v[146:149], v1, s[14:15] offset:3072
	v_cvt_pk_bf16_f32 v50, v2, v3
	v_cvt_pk_bf16_f32 v51, v4, v5
	v_cvt_pk_bf16_f32 v52, v6, v7
	v_cvt_pk_bf16_f32 v53, v8, v9
	v_cvt_pk_bf16_f32 v54, v10, v11
	v_cvt_pk_bf16_f32 v55, v12, v13
	v_cvt_pk_bf16_f32 v56, v14, v15
	v_cvt_pk_bf16_f32 v57, v16, v17
	global_load_dwordx4 v[98:101], v1, s[8:9]
	global_load_dwordx4 v[102:105], v1, s[8:9] offset:1024
	global_load_dwordx4 v[106:109], v1, s[8:9] offset:2048
	global_load_dwordx4 v[110:113], v1, s[8:9] offset:3072
	global_load_dwordx4 v[114:117], v1, s[18:19]
	v_mfma_f32_32x32x16_bf16 v[18:33], v[58:61], v[50:53], 0
	v_mfma_f32_32x32x16_bf16 v[34:49], v[66:69], v[50:53], 0
	s_add_u32 s16, s16, 0x8000
	s_addc_u32 s17, s17, 0
	s_add_u32 s14, s14, 0x8000
	s_addc_u32 s15, s15, 0
	s_add_u32 s8, s8, 0x8000
	s_addc_u32 s9, s9, 0
	s_add_u32 s18, s18, 0x2000
	s_addc_u32 s19, s19, 0
	v_mfma_f32_32x32x16_bf16 v[18:33], v[62:65], v[54:57], v[18:33]
	v_mfma_f32_32x32x16_bf16 v[34:49], v[70:73], v[54:57], v[34:49]
	v_mul_f32_e32 v2, v190, v2
	v_mul_f32_e32 v3, v190, v3
	v_mul_f32_e32 v4, v190, v4
	v_mul_f32_e32 v5, v190, v5
	v_mul_f32_e32 v6, v190, v6
	v_mul_f32_e32 v7, v190, v7
	v_mul_f32_e32 v8, v190, v8
	v_mul_f32_e32 v9, v190, v9
	v_mul_f32_e32 v10, v190, v10
	v_mul_f32_e32 v11, v190, v11
	v_mul_f32_e32 v12, v190, v12
	v_mul_f32_e32 v13, v190, v13
	v_mul_f32_e32 v14, v190, v14
	v_mul_f32_e32 v15, v190, v15
	v_mul_f32_e32 v16, v190, v16
	v_mul_f32_e32 v17, v190, v17
	s_waitcnt lgkmcnt(0)
	s_cmp_eq_u32 s7, 0
	s_cbranch_scc0 .Lp2b_in_4
	v_mfma_f32_32x32x16_bf16 v[18:33], v[74:77], v[166:169], v[18:33]
	s_branch .Lp2b_in_5
.Lp2b_in_4:
	v_mfma_f32_32x32x16_bf16 v[34:49], v[74:77], v[166:169], v[34:49]
.Lp2b_in_5:
	v_mfma_f32_32x32x16_bf16 v[2:17], v[118:121], v[150:153], v[2:17]
	v_mfma_f32_32x32x16_bf16 v[2:17], v[122:125], v[154:157], v[2:17]
	v_mfma_f32_32x32x16_bf16 v[2:17], v[126:129], v[158:161], v[2:17]
	v_mfma_f32_32x32x16_bf16 v[2:17], v[130:133], v[162:165], v[2:17]
	s_nop 7
	v_cvt_pk_bf16_f32 v18, v18, v19
	v_cvt_pk_bf16_f32 v19, v20, v21
	v_cvt_pk_bf16_f32 v20, v22, v23
	v_cvt_pk_bf16_f32 v21, v24, v25
	v_cvt_pk_bf16_f32 v22, v26, v27
	v_cvt_pk_bf16_f32 v23, v28, v29
	v_cvt_pk_bf16_f32 v24, v30, v31
	v_cvt_pk_bf16_f32 v25, v32, v33
	ds_write_b128 v192, v[18:21]
	ds_write_b128 v192, v[22:25] offset:1024
	v_cvt_pk_bf16_f32 v34, v34, v35
	v_cvt_pk_bf16_f32 v35, v36, v37
	v_cvt_pk_bf16_f32 v36, v38, v39
	v_cvt_pk_bf16_f32 v37, v40, v41
	v_cvt_pk_bf16_f32 v38, v42, v43
	v_cvt_pk_bf16_f32 v39, v44, v45
	v_cvt_pk_bf16_f32 v40, v46, v47
	v_cvt_pk_bf16_f32 v41, v48, v49
	ds_write_b128 v192, v[34:37] offset:2048
	ds_write_b128 v192, v[38:41] offset:3072
	s_waitcnt lgkmcnt(0)
	s_barrier
	ds_read2st64_b64 v[18:21], v193 offset0:0 offset1:8
	ds_read2st64_b64 v[22:25], v193 offset0:16 offset1:24
	ds_read2st64_b64 v[26:29], v193 offset0:32 offset1:40
	ds_read2st64_b64 v[30:33], v193 offset0:48 offset1:56
	ds_read_b128 v[150:153], v195 offset:4096
	ds_read_b128 v[154:157], v195 offset:5120
	ds_read_b128 v[158:161], v195 offset:6144
	ds_read_b128 v[162:165], v195 offset:7168
	ds_read_b128 v[166:169], v196 offset:4096
	s_waitcnt lgkmcnt(8)
	v_lshlrev_b32_e32 v178, 16, v18
	v_and_b32_e32 v179, 0xffff0000, v18
	v_lshlrev_b32_e32 v180, 16, v19
	v_and_b32_e32 v181, 0xffff0000, v19
	v_add_f32_e32 v174, 0, v178
	v_add_f32_e32 v175, 0, v179
	v_add_f32_e32 v176, 0, v180
	v_add_f32_e32 v177, 0, v181
	v_lshlrev_b32_e32 v178, 16, v20
	v_and_b32_e32 v179, 0xffff0000, v20
	v_lshlrev_b32_e32 v180, 16, v21
	v_and_b32_e32 v181, 0xffff0000, v21
	v_add_f32_e32 v174, v174, v178
	v_add_f32_e32 v175, v175, v179
	v_add_f32_e32 v176, v176, v180
	v_add_f32_e32 v177, v177, v181
	s_waitcnt lgkmcnt(7)
	v_lshlrev_b32_e32 v178, 16, v22
	v_and_b32_e32 v179, 0xffff0000, v22
	v_lshlrev_b32_e32 v180, 16, v23
	v_and_b32_e32 v181, 0xffff0000, v23
	v_add_f32_e32 v174, v174, v178
	v_add_f32_e32 v175, v175, v179
	v_add_f32_e32 v176, v176, v180
	v_add_f32_e32 v177, v177, v181
	v_lshlrev_b32_e32 v178, 16, v24
	v_and_b32_e32 v179, 0xffff0000, v24
	v_lshlrev_b32_e32 v180, 16, v25
	v_and_b32_e32 v181, 0xffff0000, v25
	v_add_f32_e32 v174, v174, v178
	v_add_f32_e32 v175, v175, v179
	v_add_f32_e32 v176, v176, v180
	v_add_f32_e32 v177, v177, v181
	s_waitcnt lgkmcnt(6)
	v_lshlrev_b32_e32 v178, 16, v26
	v_and_b32_e32 v179, 0xffff0000, v26
	v_lshlrev_b32_e32 v180, 16, v27
	v_and_b32_e32 v181, 0xffff0000, v27
	v_add_f32_e32 v174, v174, v178
	v_add_f32_e32 v175, v175, v179
	v_add_f32_e32 v176, v176, v180
	v_add_f32_e32 v177, v177, v181
	v_lshlrev_b32_e32 v178, 16, v28
	v_and_b32_e32 v179, 0xffff0000, v28
	v_lshlrev_b32_e32 v180, 16, v29
	v_and_b32_e32 v181, 0xffff0000, v29
	v_add_f32_e32 v174, v174, v178
	v_add_f32_e32 v175, v175, v179
	v_add_f32_e32 v176, v176, v180
	v_add_f32_e32 v177, v177, v181
	s_waitcnt lgkmcnt(5)
	v_lshlrev_b32_e32 v178, 16, v30
	v_and_b32_e32 v179, 0xffff0000, v30
	v_lshlrev_b32_e32 v180, 16, v31
	v_and_b32_e32 v181, 0xffff0000, v31
	v_add_f32_e32 v174, v174, v178
	v_add_f32_e32 v175, v175, v179
	v_add_f32_e32 v176, v176, v180
	v_add_f32_e32 v177, v177, v181
	v_lshlrev_b32_e32 v178, 16, v32
	v_and_b32_e32 v179, 0xffff0000, v32
	v_lshlrev_b32_e32 v180, 16, v33
	v_and_b32_e32 v181, 0xffff0000, v33
	v_add_f32_e32 v174, v174, v178
	v_add_f32_e32 v175, v175, v179
	v_add_f32_e32 v176, v176, v180
	v_add_f32_e32 v177, v177, v181
	v_mul_f32_e32 v174, v186, v174
	v_mul_f32_e32 v175, v187, v175
	v_mul_f32_e32 v176, v188, v176
	v_mul_f32_e32 v177, v189, v177
	v_bfe_u32 v178, v174, 16, 1
	v_bfe_u32 v179, v175, 16, 1
	v_bfe_u32 v180, v176, 16, 1
	v_bfe_u32 v181, v177, 16, 1
	v_add3_u32 v174, v174, v178, s23
	v_add3_u32 v175, v175, v179, s23
	v_add3_u32 v176, v176, v180, s23
	v_add3_u32 v177, v177, v181, s23
	global_store_short_d16_hi v197, v174, s[20:21] offset:-4096
	global_store_short_d16_hi v197, v175, s[20:21]
	global_store_short_d16_hi v198, v176, s[20:21] offset:-4096
	global_store_short_d16_hi v198, v177, s[20:21]
	s_add_u32 s20, s20, 0x40000
	s_addc_u32 s21, s21, 0
	s_waitcnt vmcnt(9)
	s_andn2_b64 vcc, exec, s[34:35]
	s_cbranch_vccnz .Lp2b_sv_6
	ds_write_b128 v194, v[170:173]
	global_load_dwordx4 v[170:173], v1, s[16:17]
.Lp2b_sv_6:
	global_load_dwordx4 v[118:121], v1, s[14:15]
	global_load_dwordx4 v[122:125], v1, s[14:15] offset:1024
	global_load_dwordx4 v[126:129], v1, s[14:15] offset:2048
	global_load_dwordx4 v[130:133], v1, s[14:15] offset:3072
	v_cvt_pk_bf16_f32 v50, v2, v3
	v_cvt_pk_bf16_f32 v51, v4, v5
	v_cvt_pk_bf16_f32 v52, v6, v7
	v_cvt_pk_bf16_f32 v53, v8, v9
	v_cvt_pk_bf16_f32 v54, v10, v11
	v_cvt_pk_bf16_f32 v55, v12, v13
	v_cvt_pk_bf16_f32 v56, v14, v15
	v_cvt_pk_bf16_f32 v57, v16, v17
	global_load_dwordx4 v[58:61], v1, s[8:9]
	global_load_dwordx4 v[62:65], v1, s[8:9] offset:1024
	global_load_dwordx4 v[66:69], v1, s[8:9] offset:2048
	global_load_dwordx4 v[70:73], v1, s[8:9] offset:3072
	global_load_dwordx4 v[74:77], v1, s[18:19]
	v_mfma_f32_32x32x16_bf16 v[18:33], v[78:81], v[50:53], 0
	v_mfma_f32_32x32x16_bf16 v[34:49], v[86:89], v[50:53], 0
	s_add_u32 s16, s16, 0x8000
	s_addc_u32 s17, s17, 0
	s_add_u32 s14, s14, 0x8000
	s_addc_u32 s15, s15, 0
	s_add_u32 s8, s8, 0x8000
	s_addc_u32 s9, s9, 0
	s_add_u32 s18, s18, 0x2000
	s_addc_u32 s19, s19, 0
	v_mfma_f32_32x32x16_bf16 v[18:33], v[82:85], v[54:57], v[18:33]
	v_mfma_f32_32x32x16_bf16 v[34:49], v[90:93], v[54:57], v[34:49]
	v_mul_f32_e32 v2, v190, v2
	v_mul_f32_e32 v3, v190, v3
	v_mul_f32_e32 v4, v190, v4
	v_mul_f32_e32 v5, v190, v5
	v_mul_f32_e32 v6, v190, v6
	v_mul_f32_e32 v7, v190, v7
	v_mul_f32_e32 v8, v190, v8
	v_mul_f32_e32 v9, v190, v9
	v_mul_f32_e32 v10, v190, v10
	v_mul_f32_e32 v11, v190, v11
	v_mul_f32_e32 v12, v190, v12
	v_mul_f32_e32 v13, v190, v13
	v_mul_f32_e32 v14, v190, v14
	v_mul_f32_e32 v15, v190, v15
	v_mul_f32_e32 v16, v190, v16
	v_mul_f32_e32 v17, v190, v17
	s_waitcnt lgkmcnt(0)
	s_cmp_eq_u32 s7, 0
	s_cbranch_scc0 .Lp2b_in_7
	v_mfma_f32_32x32x16_bf16 v[18:33], v[94:97], v[166:169], v[18:33]
	s_branch .Lp2b_in_8
.Lp2b_in_7:
	v_mfma_f32_32x32x16_bf16 v[34:49], v[94:97], v[166:169], v[34:49]
.Lp2b_in_8:
	v_mfma_f32_32x32x16_bf16 v[2:17], v[134:137], v[150:153], v[2:17]
	v_mfma_f32_32x32x16_bf16 v[2:17], v[138:141], v[154:157], v[2:17]
	v_mfma_f32_32x32x16_bf16 v[2:17], v[142:145], v[158:161], v[2:17]
	v_mfma_f32_32x32x16_bf16 v[2:17], v[146:149], v[162:165], v[2:17]
	s_nop 7
	v_cvt_pk_bf16_f32 v18, v18, v19
	v_cvt_pk_bf16_f32 v19, v20, v21
	v_cvt_pk_bf16_f32 v20, v22, v23
	v_cvt_pk_bf16_f32 v21, v24, v25
	v_cvt_pk_bf16_f32 v22, v26, v27
	v_cvt_pk_bf16_f32 v23, v28, v29
	v_cvt_pk_bf16_f32 v24, v30, v31
	v_cvt_pk_bf16_f32 v25, v32, v33
	ds_write_b128 v192, v[18:21] offset:32768
	ds_write_b128 v192, v[22:25] offset:33792
	v_cvt_pk_bf16_f32 v34, v34, v35
	v_cvt_pk_bf16_f32 v35, v36, v37
	v_cvt_pk_bf16_f32 v36, v38, v39
	v_cvt_pk_bf16_f32 v37, v40, v41
	v_cvt_pk_bf16_f32 v38, v42, v43
	v_cvt_pk_bf16_f32 v39, v44, v45
	v_cvt_pk_bf16_f32 v40, v46, v47
	v_cvt_pk_bf16_f32 v41, v48, v49
	ds_write_b128 v192, v[34:37] offset:34816
	ds_write_b128 v192, v[38:41] offset:35840
	s_waitcnt lgkmcnt(0)
	s_barrier
	ds_read2st64_b64 v[18:21], v193 offset0:64 offset1:72
	ds_read2st64_b64 v[22:25], v193 offset0:80 offset1:88
	ds_read2st64_b64 v[26:29], v193 offset0:96 offset1:104
	ds_read2st64_b64 v[30:33], v193 offset0:112 offset1:120
	ds_read_b128 v[150:153], v195
	ds_read_b128 v[154:157], v195 offset:1024
	ds_read_b128 v[158:161], v195 offset:2048
	ds_read_b128 v[162:165], v195 offset:3072
	ds_read_b128 v[166:169], v196
	s_waitcnt lgkmcnt(8)
	v_lshlrev_b32_e32 v178, 16, v18
	v_and_b32_e32 v179, 0xffff0000, v18
	v_lshlrev_b32_e32 v180, 16, v19
	v_and_b32_e32 v181, 0xffff0000, v19
	v_add_f32_e32 v174, 0, v178
	v_add_f32_e32 v175, 0, v179
	v_add_f32_e32 v176, 0, v180
	v_add_f32_e32 v177, 0, v181
	v_lshlrev_b32_e32 v178, 16, v20
	v_and_b32_e32 v179, 0xffff0000, v20
	v_lshlrev_b32_e32 v180, 16, v21
	v_and_b32_e32 v181, 0xffff0000, v21
	v_add_f32_e32 v174, v174, v178
	v_add_f32_e32 v175, v175, v179
	v_add_f32_e32 v176, v176, v180
	v_add_f32_e32 v177, v177, v181
	s_waitcnt lgkmcnt(7)
	v_lshlrev_b32_e32 v178, 16, v22
	v_and_b32_e32 v179, 0xffff0000, v22
	v_lshlrev_b32_e32 v180, 16, v23
	v_and_b32_e32 v181, 0xffff0000, v23
	v_add_f32_e32 v174, v174, v178
	v_add_f32_e32 v175, v175, v179
	v_add_f32_e32 v176, v176, v180
	v_add_f32_e32 v177, v177, v181
	v_lshlrev_b32_e32 v178, 16, v24
	v_and_b32_e32 v179, 0xffff0000, v24
	v_lshlrev_b32_e32 v180, 16, v25
	v_and_b32_e32 v181, 0xffff0000, v25
	v_add_f32_e32 v174, v174, v178
	v_add_f32_e32 v175, v175, v179
	v_add_f32_e32 v176, v176, v180
	v_add_f32_e32 v177, v177, v181
	s_waitcnt lgkmcnt(6)
	v_lshlrev_b32_e32 v178, 16, v26
	v_and_b32_e32 v179, 0xffff0000, v26
	v_lshlrev_b32_e32 v180, 16, v27
	v_and_b32_e32 v181, 0xffff0000, v27
	v_add_f32_e32 v174, v174, v178
	v_add_f32_e32 v175, v175, v179
	v_add_f32_e32 v176, v176, v180
	v_add_f32_e32 v177, v177, v181
	v_lshlrev_b32_e32 v178, 16, v28
	v_and_b32_e32 v179, 0xffff0000, v28
	v_lshlrev_b32_e32 v180, 16, v29
	v_and_b32_e32 v181, 0xffff0000, v29
	v_add_f32_e32 v174, v174, v178
	v_add_f32_e32 v175, v175, v179
	v_add_f32_e32 v176, v176, v180
	v_add_f32_e32 v177, v177, v181
	s_waitcnt lgkmcnt(5)
	v_lshlrev_b32_e32 v178, 16, v30
	v_and_b32_e32 v179, 0xffff0000, v30
	v_lshlrev_b32_e32 v180, 16, v31
	v_and_b32_e32 v181, 0xffff0000, v31
	v_add_f32_e32 v174, v174, v178
	v_add_f32_e32 v175, v175, v179
	v_add_f32_e32 v176, v176, v180
	v_add_f32_e32 v177, v177, v181
	v_lshlrev_b32_e32 v178, 16, v32
	v_and_b32_e32 v179, 0xffff0000, v32
	v_lshlrev_b32_e32 v180, 16, v33
	v_and_b32_e32 v181, 0xffff0000, v33
	v_add_f32_e32 v174, v174, v178
	v_add_f32_e32 v175, v175, v179
	v_add_f32_e32 v176, v176, v180
	v_add_f32_e32 v177, v177, v181
	v_mul_f32_e32 v174, v186, v174
	v_mul_f32_e32 v175, v187, v175
	v_mul_f32_e32 v176, v188, v176
	v_mul_f32_e32 v177, v189, v177
	v_bfe_u32 v178, v174, 16, 1
	v_bfe_u32 v179, v175, 16, 1
	v_bfe_u32 v180, v176, 16, 1
	v_bfe_u32 v181, v177, 16, 1
	v_add3_u32 v174, v174, v178, s23
	v_add3_u32 v175, v175, v179, s23
	v_add3_u32 v176, v176, v180, s23
	v_add3_u32 v177, v177, v181, s23
	global_store_short_d16_hi v197, v174, s[20:21] offset:-4096
	global_store_short_d16_hi v197, v175, s[20:21]
	global_store_short_d16_hi v198, v176, s[20:21] offset:-4096
	global_store_short_d16_hi v198, v177, s[20:21]
	s_add_u32 s20, s20, 0x40000
	s_addc_u32 s21, s21, 0
	s_waitcnt vmcnt(9)
	s_andn2_b64 vcc, exec, s[34:35]
	s_cbranch_vccnz .Lp2b_sv_9
	ds_write_b128 v194, v[170:173] offset:4096
	global_load_dwordx4 v[170:173], v1, s[16:17]
.Lp2b_sv_9:
	global_load_dwordx4 v[134:137], v1, s[14:15]
	global_load_dwordx4 v[138:141], v1, s[14:15] offset:1024
	global_load_dwordx4 v[142:145], v1, s[14:15] offset:2048
	global_load_dwordx4 v[146:149], v1, s[14:15] offset:3072
	v_cvt_pk_bf16_f32 v50, v2, v3
	v_cvt_pk_bf16_f32 v51, v4, v5
	v_cvt_pk_bf16_f32 v52, v6, v7
	v_cvt_pk_bf16_f32 v53, v8, v9
	v_cvt_pk_bf16_f32 v54, v10, v11
	v_cvt_pk_bf16_f32 v55, v12, v13
	v_cvt_pk_bf16_f32 v56, v14, v15
	v_cvt_pk_bf16_f32 v57, v16, v17
	global_load_dwordx4 v[78:81], v1, s[8:9]
	global_load_dwordx4 v[82:85], v1, s[8:9] offset:1024
	global_load_dwordx4 v[86:89], v1, s[8:9] offset:2048
	global_load_dwordx4 v[90:93], v1, s[8:9] offset:3072
	global_load_dwordx4 v[94:97], v1, s[18:19]
	v_mfma_f32_32x32x16_bf16 v[18:33], v[98:101], v[50:53], 0
	v_mfma_f32_32x32x16_bf16 v[34:49], v[106:109], v[50:53], 0
	s_add_u32 s16, s16, 0x8000
	s_addc_u32 s17, s17, 0
	s_add_u32 s14, s14, 0x8000
	s_addc_u32 s15, s15, 0
	s_add_u32 s8, s8, 0x8000
	s_addc_u32 s9, s9, 0
	s_add_u32 s18, s18, 0x2000
	s_addc_u32 s19, s19, 0
	v_mfma_f32_32x32x16_bf16 v[18:33], v[102:105], v[54:57], v[18:33]
	v_mfma_f32_32x32x16_bf16 v[34:49], v[110:113], v[54:57], v[34:49]
	v_mul_f32_e32 v2, v190, v2
	v_mul_f32_e32 v3, v190, v3
	v_mul_f32_e32 v4, v190, v4
	v_mul_f32_e32 v5, v190, v5
	v_mul_f32_e32 v6, v190, v6
	v_mul_f32_e32 v7, v190, v7
	v_mul_f32_e32 v8, v190, v8
	v_mul_f32_e32 v9, v190, v9
	v_mul_f32_e32 v10, v190, v10
	v_mul_f32_e32 v11, v190, v11
	v_mul_f32_e32 v12, v190, v12
	v_mul_f32_e32 v13, v190, v13
	v_mul_f32_e32 v14, v190, v14
	v_mul_f32_e32 v15, v190, v15
	v_mul_f32_e32 v16, v190, v16
	v_mul_f32_e32 v17, v190, v17
	s_waitcnt lgkmcnt(0)
	s_cmp_eq_u32 s7, 0
	s_cbranch_scc0 .Lp2b_in_10
	v_mfma_f32_32x32x16_bf16 v[18:33], v[114:117], v[166:169], v[18:33]
	s_branch .Lp2b_in_11
.Lp2b_in_10:
	v_mfma_f32_32x32x16_bf16 v[34:49], v[114:117], v[166:169], v[34:49]

.Lp2b_sv_12:
	global_load_dwordx4 v[118:121], v1, s[14:15]
	global_load_dwordx4 v[122:125], v1, s[14:15] offset:1024
	global_load_dwordx4 v[126:129], v1, s[14:15] offset:2048
	global_load_dwordx4 v[130:133], v1, s[14:15] offset:3072
	v_cvt_pk_bf16_f32 v50, v2, v3
	v_cvt_pk_bf16_f32 v51, v4, v5
	v_cvt_pk_bf16_f32 v52, v6, v7
	v_cvt_pk_bf16_f32 v53, v8, v9
	v_cvt_pk_bf16_f32 v54, v10, v11
	v_cvt_pk_bf16_f32 v55, v12, v13
	v_cvt_pk_bf16_f32 v56, v14, v15
	v_cvt_pk_bf16_f32 v57, v16, v17
	global_load_dwordx4 v[98:101], v1, s[8:9]
	global_load_dwordx4 v[102:105], v1, s[8:9] offset:1024
	global_load_dwordx4 v[106:109], v1, s[8:9] offset:2048
	global_load_dwordx4 v[110:113], v1, s[8:9] offset:3072
	global_load_dwordx4 v[114:117], v1, s[18:19]
	v_mfma_f32_32x32x16_bf16 v[18:33], v[58:61], v[50:53], 0
	v_mfma_f32_32x32x16_bf16 v[34:49], v[66:69], v[50:53], 0
	s_add_u32 s16, s16, 0x8000
	s_addc_u32 s17, s17, 0
	s_add_u32 s14, s14, 0x8000
	s_addc_u32 s15, s15, 0
	s_add_u32 s8, s8, 0x8000
	s_addc_u32 s9, s9, 0
	s_add_u32 s18, s18, 0x2000
	s_addc_u32 s19, s19, 0
	v_mfma_f32_32x32x16_bf16 v[18:33], v[62:65], v[54:57], v[18:33]
	v_mfma_f32_32x32x16_bf16 v[34:49], v[70:73], v[54:57], v[34:49]
	v_mul_f32_e32 v2, v190, v2
	v_mul_f32_e32 v3, v190, v3
	v_mul_f32_e32 v4, v190, v4
	v_mul_f32_e32 v5, v190, v5
	v_mul_f32_e32 v6, v190, v6
	v_mul_f32_e32 v7, v190, v7
	v_mul_f32_e32 v8, v190, v8
	v_mul_f32_e32 v9, v190, v9
	v_mul_f32_e32 v10, v190, v10
	v_mul_f32_e32 v11, v190, v11
	v_mul_f32_e32 v12, v190, v12
	v_mul_f32_e32 v13, v190, v13
	v_mul_f32_e32 v14, v190, v14
	v_mul_f32_e32 v15, v190, v15
	v_mul_f32_e32 v16, v190, v16
	v_mul_f32_e32 v17, v190, v17
	s_waitcnt lgkmcnt(0)
	s_cmp_eq_u32 s7, 0
	s_cbranch_scc0 .Lp2b_in_13
	v_mfma_f32_32x32x16_bf16 v[18:33], v[74:77], v[166:169], v[18:33]
	s_branch .Lp2b_in_14

.Lp2b_sv_15:
	global_load_dwordx4 v[134:137], v1, s[14:15]
	global_load_dwordx4 v[138:141], v1, s[14:15] offset:1024
	global_load_dwordx4 v[142:145], v1, s[14:15] offset:2048
	global_load_dwordx4 v[146:149], v1, s[14:15] offset:3072
	v_cvt_pk_bf16_f32 v50, v2, v3
	v_cvt_pk_bf16_f32 v51, v4, v5
	v_cvt_pk_bf16_f32 v52, v6, v7
	v_cvt_pk_bf16_f32 v53, v8, v9
	v_cvt_pk_bf16_f32 v54, v10, v11
	v_cvt_pk_bf16_f32 v55, v12, v13
	v_cvt_pk_bf16_f32 v56, v14, v15
	v_cvt_pk_bf16_f32 v57, v16, v17
	global_load_dwordx4 v[58:61], v1, s[8:9]
	global_load_dwordx4 v[62:65], v1, s[8:9] offset:1024
	global_load_dwordx4 v[66:69], v1, s[8:9] offset:2048
	global_load_dwordx4 v[70:73], v1, s[8:9] offset:3072
	global_load_dwordx4 v[74:77], v1, s[18:19]
	v_mfma_f32_32x32x16_bf16 v[18:33], v[78:81], v[50:53], 0
	v_mfma_f32_32x32x16_bf16 v[34:49], v[86:89], v[50:53], 0
	s_add_u32 s16, s16, 0x8000
	s_addc_u32 s17, s17, 0
	s_add_u32 s14, s14, 0x8000
	s_addc_u32 s15, s15, 0
	s_add_u32 s8, s8, 0x8000
	s_addc_u32 s9, s9, 0
	s_add_u32 s18, s18, 0x2000
	s_addc_u32 s19, s19, 0
	v_mfma_f32_32x32x16_bf16 v[18:33], v[82:85], v[54:57], v[18:33]
	v_mfma_f32_32x32x16_bf16 v[34:49], v[90:93], v[54:57], v[34:49]
	v_mul_f32_e32 v2, v190, v2
	v_mul_f32_e32 v3, v190, v3
	v_mul_f32_e32 v4, v190, v4
	v_mul_f32_e32 v5, v190, v5
	v_mul_f32_e32 v6, v190, v6
	v_mul_f32_e32 v7, v190, v7
	v_mul_f32_e32 v8, v190, v8
	v_mul_f32_e32 v9, v190, v9
	v_mul_f32_e32 v10, v190, v10
	v_mul_f32_e32 v11, v190, v11
	v_mul_f32_e32 v12, v190, v12
	v_mul_f32_e32 v13, v190, v13
	v_mul_f32_e32 v14, v190, v14
	v_mul_f32_e32 v15, v190, v15
	v_mul_f32_e32 v16, v190, v16
	v_mul_f32_e32 v17, v190, v17
	s_waitcnt lgkmcnt(0)
	s_cmp_eq_u32 s7, 0
	s_cbranch_scc0 .Lp2b_in_16
	v_mfma_f32_32x32x16_bf16 v[18:33], v[94:97], v[166:169], v[18:33]
	s_branch .Lp2b_in_17

.Lp2b_sv_18:
	global_load_dwordx4 v[118:121], v1, s[14:15]
	global_load_dwordx4 v[122:125], v1, s[14:15] offset:1024
	global_load_dwordx4 v[126:129], v1, s[14:15] offset:2048
	global_load_dwordx4 v[130:133], v1, s[14:15] offset:3072
	v_cvt_pk_bf16_f32 v50, v2, v3
	v_cvt_pk_bf16_f32 v51, v4, v5
	v_cvt_pk_bf16_f32 v52, v6, v7
	v_cvt_pk_bf16_f32 v53, v8, v9
	v_cvt_pk_bf16_f32 v54, v10, v11
	v_cvt_pk_bf16_f32 v55, v12, v13
	v_cvt_pk_bf16_f32 v56, v14, v15
	v_cvt_pk_bf16_f32 v57, v16, v17
	global_load_dwordx4 v[78:81], v1, s[8:9]
	global_load_dwordx4 v[82:85], v1, s[8:9] offset:1024
	global_load_dwordx4 v[86:89], v1, s[8:9] offset:2048
	global_load_dwordx4 v[90:93], v1, s[8:9] offset:3072
	global_load_dwordx4 v[94:97], v1, s[18:19]
	v_mfma_f32_32x32x16_bf16 v[18:33], v[98:101], v[50:53], 0
	v_mfma_f32_32x32x16_bf16 v[34:49], v[106:109], v[50:53], 0
	s_add_u32 s16, s16, 0x8000
	s_addc_u32 s17, s17, 0
	s_add_u32 s14, s14, 0x8000
	s_addc_u32 s15, s15, 0
	s_add_u32 s8, s8, 0x8000
	s_addc_u32 s9, s9, 0
	s_add_u32 s18, s18, 0x2000
	s_addc_u32 s19, s19, 0
	v_mfma_f32_32x32x16_bf16 v[18:33], v[102:105], v[54:57], v[18:33]
	v_mfma_f32_32x32x16_bf16 v[34:49], v[110:113], v[54:57], v[34:49]
	v_mul_f32_e32 v2, v190, v2
	v_mul_f32_e32 v3, v190, v3
	v_mul_f32_e32 v4, v190, v4
	v_mul_f32_e32 v5, v190, v5
	v_mul_f32_e32 v6, v190, v6
	v_mul_f32_e32 v7, v190, v7
	v_mul_f32_e32 v8, v190, v8
	v_mul_f32_e32 v9, v190, v9
	v_mul_f32_e32 v10, v190, v10
	v_mul_f32_e32 v11, v190, v11
	v_mul_f32_e32 v12, v190, v12
	v_mul_f32_e32 v13, v190, v13
	v_mul_f32_e32 v14, v190, v14
	v_mul_f32_e32 v15, v190, v15
	v_mul_f32_e32 v16, v190, v16
	v_mul_f32_e32 v17, v190, v17
	s_waitcnt lgkmcnt(0)
	s_cmp_eq_u32 s7, 0
	s_cbranch_scc0 .Lp2b_in_19
	v_mfma_f32_32x32x16_bf16 v[18:33], v[114:117], v[166:169], v[18:33]
	s_branch .Lp2b_in_20

; __device__ __forceinline__ void scan_phase(const bf16* q, const bf16* kdT, const bf16* vT, const bf16* Pp, bf16* o, LAS unsigned char* lds, int bid, int G, int wave, int lane, int tid) {
;     ...
;         for (int i = 0; i < 60; i += 6) { SCAN_STEP(0, 2, 0, 1, i); SCAN_STEP(1, 0, 1, 0, i + 1); SCAN_STEP(2, 1, 0, 1, i + 2); SCAN_STEP(0, 2, 1, 0, i + 3); SCAN_STEP(1, 0, 0, 1, i + 4); SCAN_STEP(2, 1, 1, 0, i + 5); }
.Lp2b_in_20:
	v_mfma_f32_32x32x16_bf16 v[2:17], v[134:137], v[150:153], v[2:17]
	v_mfma_f32_32x32x16_bf16 v[2:17], v[138:141], v[154:157], v[2:17]
	v_mfma_f32_32x32x16_bf16 v[2:17], v[142:145], v[158:161], v[2:17]
	v_mfma_f32_32x32x16_bf16 v[2:17], v[146:149], v[162:165], v[2:17]
	s_nop 7
	v_cvt_pk_bf16_f32 v18, v18, v19
	v_cvt_pk_bf16_f32 v19, v20, v21
	v_cvt_pk_bf16_f32 v20, v22, v23
	v_cvt_pk_bf16_f32 v21, v24, v25
	v_cvt_pk_bf16_f32 v22, v26, v27
	v_cvt_pk_bf16_f32 v23, v28, v29
	v_cvt_pk_bf16_f32 v24, v30, v31
	v_cvt_pk_bf16_f32 v25, v32, v33
	ds_write_b128 v192, v[18:21] offset:32768
	ds_write_b128 v192, v[22:25] offset:33792
	v_cvt_pk_bf16_f32 v34, v34, v35
	v_cvt_pk_bf16_f32 v35, v36, v37
	v_cvt_pk_bf16_f32 v36, v38, v39
	v_cvt_pk_bf16_f32 v37, v40, v41
	v_cvt_pk_bf16_f32 v38, v42, v43
	v_cvt_pk_bf16_f32 v39, v44, v45
	v_cvt_pk_bf16_f32 v40, v46, v47
	v_cvt_pk_bf16_f32 v41, v48, v49
	ds_write_b128 v192, v[34:37] offset:34816
	ds_write_b128 v192, v[38:41] offset:35840
	s_waitcnt lgkmcnt(0)
	s_barrier
	ds_read2st64_b64 v[18:21], v193 offset0:64 offset1:72
	ds_read2st64_b64 v[22:25], v193 offset0:80 offset1:88
	ds_read2st64_b64 v[26:29], v193 offset0:96 offset1:104
	ds_read2st64_b64 v[30:33], v193 offset0:112 offset1:120
	ds_read_b128 v[150:153], v195
	ds_read_b128 v[154:157], v195 offset:1024
	ds_read_b128 v[158:161], v195 offset:2048
	ds_read_b128 v[162:165], v195 offset:3072
	ds_read_b128 v[166:169], v196
	s_waitcnt lgkmcnt(8)
	v_lshlrev_b32_e32 v178, 16, v18
	v_and_b32_e32 v179, 0xffff0000, v18
	v_lshlrev_b32_e32 v180, 16, v19
	v_and_b32_e32 v181, 0xffff0000, v19
	v_add_f32_e32 v174, 0, v178
	v_add_f32_e32 v175, 0, v179
	v_add_f32_e32 v176, 0, v180
	v_add_f32_e32 v177, 0, v181
	v_lshlrev_b32_e32 v178, 16, v20
	v_and_b32_e32 v179, 0xffff0000, v20
	v_lshlrev_b32_e32 v180, 16, v21
	v_and_b32_e32 v181, 0xffff0000, v21
	v_add_f32_e32 v174, v174, v178
	v_add_f32_e32 v175, v175, v179
	v_add_f32_e32 v176, v176, v180
	v_add_f32_e32 v177, v177, v181
	s_waitcnt lgkmcnt(7)
	v_lshlrev_b32_e32 v178, 16, v22
	v_and_b32_e32 v179, 0xffff0000, v22
	v_lshlrev_b32_e32 v180, 16, v23
	v_and_b32_e32 v181, 0xffff0000, v23
	v_add_f32_e32 v174, v174, v178
	v_add_f32_e32 v175, v175, v179
	v_add_f32_e32 v176, v176, v180
	v_add_f32_e32 v177, v177, v181
	v_lshlrev_b32_e32 v178, 16, v24
	v_and_b32_e32 v179, 0xffff0000, v24
	v_lshlrev_b32_e32 v180, 16, v25
	v_and_b32_e32 v181, 0xffff0000, v25
	v_add_f32_e32 v174, v174, v178
	v_add_f32_e32 v175, v175, v179
	v_add_f32_e32 v176, v176, v180
	v_add_f32_e32 v177, v177, v181
	s_waitcnt lgkmcnt(6)
	v_lshlrev_b32_e32 v178, 16, v26
	v_and_b32_e32 v179, 0xffff0000, v26
	v_lshlrev_b32_e32 v180, 16, v27
	v_and_b32_e32 v181, 0xffff0000, v27
	v_add_f32_e32 v174, v174, v178
	v_add_f32_e32 v175, v175, v179
	v_add_f32_e32 v176, v176, v180
	v_add_f32_e32 v177, v177, v181
	v_lshlrev_b32_e32 v178, 16, v28
	v_and_b32_e32 v179, 0xffff0000, v28
	v_lshlrev_b32_e32 v180, 16, v29
	v_and_b32_e32 v181, 0xffff0000, v29
	v_add_f32_e32 v174, v174, v178
	v_add_f32_e32 v175, v175, v179
	v_add_f32_e32 v176, v176, v180
	v_add_f32_e32 v177, v177, v181
	s_waitcnt lgkmcnt(5)
	v_lshlrev_b32_e32 v178, 16, v30
	v_and_b32_e32 v179, 0xffff0000, v30
	v_lshlrev_b32_e32 v180, 16, v31
	v_and_b32_e32 v181, 0xffff0000, v31
	v_add_f32_e32 v174, v174, v178
	v_add_f32_e32 v175, v175, v179
	v_add_f32_e32 v176, v176, v180
	v_add_f32_e32 v177, v177, v181
	v_lshlrev_b32_e32 v178, 16, v32
	v_and_b32_e32 v179, 0xffff0000, v32
	v_lshlrev_b32_e32 v180, 16, v33
	v_and_b32_e32 v181, 0xffff0000, v33
	v_add_f32_e32 v174, v174, v178
	v_add_f32_e32 v175, v175, v179
	v_add_f32_e32 v176, v176, v180
	v_add_f32_e32 v177, v177, v181
	v_mul_f32_e32 v174, v186, v174
	v_mul_f32_e32 v175, v187, v175
	v_mul_f32_e32 v176, v188, v176
	v_mul_f32_e32 v177, v189, v177
	v_bfe_u32 v178, v174, 16, 1
	v_bfe_u32 v179, v175, 16, 1
	v_bfe_u32 v180, v176, 16, 1
	v_bfe_u32 v181, v177, 16, 1
	v_add3_u32 v174, v174, v178, s23
	v_add3_u32 v175, v175, v179, s23
	v_add3_u32 v176, v176, v180, s23
	v_add3_u32 v177, v177, v181, s23
	global_store_short_d16_hi v197, v174, s[20:21] offset:-4096
	global_store_short_d16_hi v197, v175, s[20:21]
	global_store_short_d16_hi v198, v176, s[20:21] offset:-4096
	global_store_short_d16_hi v198, v177, s[20:21]
	s_add_u32 s20, s20, 0x40000
	s_addc_u32 s21, s21, 0
	s_add_i32 s22, s22, 1
	s_cmp_lt_u32 s22, 10
	s_cbranch_scc1 .Lp2b_loop
	s_waitcnt vmcnt(9)
	s_andn2_b64 vcc, exec, s[34:35]
	s_cbranch_vccnz .Lp2b_sv_21
	ds_write_b128 v194, v[170:173] offset:4096
	global_load_dwordx4 v[170:173], v1, s[16:17]

; __device__ __forceinline__ void scan_phase(const bf16* q, const bf16* kdT, const bf16* vT, const bf16* Pp, bf16* o, LAS unsigned char* lds, int bid, int G, int wave, int lane, int tid) {
;     ...
;         SCAN_STEP(0, 2, 0, 1, 60); SCAN_STEP(1, 0, 1, 0, 61); SCAN_STEP(2, 1, 0, 1, 62); SCAN_STEP(0, 2, 1, 0, 63);
.Lp2b_in_26:
	v_mfma_f32_32x32x16_bf16 v[2:17], v[134:137], v[150:153], v[2:17]
	v_mfma_f32_32x32x16_bf16 v[2:17], v[138:141], v[154:157], v[2:17]
	v_mfma_f32_32x32x16_bf16 v[2:17], v[142:145], v[158:161], v[2:17]
	v_mfma_f32_32x32x16_bf16 v[2:17], v[146:149], v[162:165], v[2:17]
	s_nop 7
	v_cvt_pk_bf16_f32 v18, v18, v19
	v_cvt_pk_bf16_f32 v19, v20, v21
	v_cvt_pk_bf16_f32 v20, v22, v23
	v_cvt_pk_bf16_f32 v21, v24, v25
	v_cvt_pk_bf16_f32 v22, v26, v27
	v_cvt_pk_bf16_f32 v23, v28, v29
	v_cvt_pk_bf16_f32 v24, v30, v31
	v_cvt_pk_bf16_f32 v25, v32, v33
	ds_write_b128 v192, v[18:21] offset:32768
	ds_write_b128 v192, v[22:25] offset:33792
	v_cvt_pk_bf16_f32 v34, v34, v35
	v_cvt_pk_bf16_f32 v35, v36, v37
	v_cvt_pk_bf16_f32 v36, v38, v39
	v_cvt_pk_bf16_f32 v37, v40, v41
	v_cvt_pk_bf16_f32 v38, v42, v43
	v_cvt_pk_bf16_f32 v39, v44, v45
	v_cvt_pk_bf16_f32 v40, v46, v47
	v_cvt_pk_bf16_f32 v41, v48, v49
	ds_write_b128 v192, v[34:37] offset:34816
	ds_write_b128 v192, v[38:41] offset:35840
	s_waitcnt lgkmcnt(0)
	s_barrier
	ds_read2st64_b64 v[18:21], v193 offset0:64 offset1:72
	ds_read2st64_b64 v[22:25], v193 offset0:80 offset1:88
	ds_read2st64_b64 v[26:29], v193 offset0:96 offset1:104
	ds_read2st64_b64 v[30:33], v193 offset0:112 offset1:120
	ds_read_b128 v[150:153], v195
	ds_read_b128 v[154:157], v195 offset:1024
	ds_read_b128 v[158:161], v195 offset:2048
	ds_read_b128 v[162:165], v195 offset:3072
	ds_read_b128 v[166:169], v196
	s_waitcnt lgkmcnt(8)
	v_lshlrev_b32_e32 v178, 16, v18
	v_and_b32_e32 v179, 0xffff0000, v18
	v_lshlrev_b32_e32 v180, 16, v19
	v_and_b32_e32 v181, 0xffff0000, v19
	v_add_f32_e32 v174, 0, v178
	v_add_f32_e32 v175, 0, v179
	v_add_f32_e32 v176, 0, v180
	v_add_f32_e32 v177, 0, v181
	v_lshlrev_b32_e32 v178, 16, v20
	v_and_b32_e32 v179, 0xffff0000, v20
	v_lshlrev_b32_e32 v180, 16, v21
	v_and_b32_e32 v181, 0xffff0000, v21
	v_add_f32_e32 v174, v174, v178
	v_add_f32_e32 v175, v175, v179
	v_add_f32_e32 v176, v176, v180
	v_add_f32_e32 v177, v177, v181
	s_waitcnt lgkmcnt(7)
	v_lshlrev_b32_e32 v178, 16, v22
	v_and_b32_e32 v179, 0xffff0000, v22
	v_lshlrev_b32_e32 v180, 16, v23
	v_and_b32_e32 v181, 0xffff0000, v23
	v_add_f32_e32 v174, v174, v178
	v_add_f32_e32 v175, v175, v179
	v_add_f32_e32 v176, v176, v180
	v_add_f32_e32 v177, v177, v181
	v_lshlrev_b32_e32 v178, 16, v24
	v_and_b32_e32 v179, 0xffff0000, v24
	v_lshlrev_b32_e32 v180, 16, v25
	v_and_b32_e32 v181, 0xffff0000, v25
	v_add_f32_e32 v174, v174, v178
	v_add_f32_e32 v175, v175, v179
	v_add_f32_e32 v176, v176, v180
	v_add_f32_e32 v177, v177, v181
	s_waitcnt lgkmcnt(6)
	v_lshlrev_b32_e32 v178, 16, v26
	v_and_b32_e32 v179, 0xffff0000, v26
	v_lshlrev_b32_e32 v180, 16, v27
	v_and_b32_e32 v181, 0xffff0000, v27
	v_add_f32_e32 v174, v174, v178
	v_add_f32_e32 v175, v175, v179
	v_add_f32_e32 v176, v176, v180
	v_add_f32_e32 v177, v177, v181
	v_lshlrev_b32_e32 v178, 16, v28
	v_and_b32_e32 v179, 0xffff0000, v28
	v_lshlrev_b32_e32 v180, 16, v29
	v_and_b32_e32 v181, 0xffff0000, v29
	v_add_f32_e32 v174, v174, v178
	v_add_f32_e32 v175, v175, v179
	v_add_f32_e32 v176, v176, v180
	v_add_f32_e32 v177, v177, v181
	s_waitcnt lgkmcnt(5)
	v_lshlrev_b32_e32 v178, 16, v30
	v_and_b32_e32 v179, 0xffff0000, v30
	v_lshlrev_b32_e32 v180, 16, v31
	v_and_b32_e32 v181, 0xffff0000, v31
	v_add_f32_e32 v174, v174, v178
	v_add_f32_e32 v175, v175, v179
	v_add_f32_e32 v176, v176, v180
	v_add_f32_e32 v177, v177, v181
	v_lshlrev_b32_e32 v178, 16, v32
	v_and_b32_e32 v179, 0xffff0000, v32
	v_lshlrev_b32_e32 v180, 16, v33
	v_and_b32_e32 v181, 0xffff0000, v33
	v_add_f32_e32 v174, v174, v178
	v_add_f32_e32 v175, v175, v179
	v_add_f32_e32 v176, v176, v180
	v_add_f32_e32 v177, v177, v181
	v_mul_f32_e32 v174, v186, v174
	v_mul_f32_e32 v175, v187, v175
	v_mul_f32_e32 v176, v188, v176
	v_mul_f32_e32 v177, v189, v177
	v_bfe_u32 v178, v174, 16, 1
	v_bfe_u32 v179, v175, 16, 1
	v_bfe_u32 v180, v176, 16, 1
	v_bfe_u32 v181, v177, 16, 1
	v_add3_u32 v174, v174, v178, s23
	v_add3_u32 v175, v175, v179, s23
	v_add3_u32 v176, v176, v180, s23
	v_add3_u32 v177, v177, v181, s23
	global_store_short_d16_hi v197, v174, s[20:21] offset:-4096
	global_store_short_d16_hi v197, v175, s[20:21]
	global_store_short_d16_hi v198, v176, s[20:21] offset:-4096
	global_store_short_d16_hi v198, v177, s[20:21]
	s_add_u32 s20, s20, 0x40000
	s_addc_u32 s21, s21, 0
	s_waitcnt vmcnt(9)
	s_andn2_b64 vcc, exec, s[34:35]
	s_cbranch_vccnz .Lp2b_sv_27
	ds_write_b128 v194, v[170:173] offset:4096
.Lp2b_sv_27:
	global_load_dwordx4 v[134:137], v1, s[14:15]
	global_load_dwordx4 v[138:141], v1, s[14:15] offset:1024
	global_load_dwordx4 v[142:145], v1, s[14:15] offset:2048
	global_load_dwordx4 v[146:149], v1, s[14:15] offset:3072
	v_cvt_pk_bf16_f32 v50, v2, v3
	v_cvt_pk_bf16_f32 v51, v4, v5
	v_cvt_pk_bf16_f32 v52, v6, v7
	v_cvt_pk_bf16_f32 v53, v8, v9
	v_cvt_pk_bf16_f32 v54, v10, v11
	v_cvt_pk_bf16_f32 v55, v12, v13
	v_cvt_pk_bf16_f32 v56, v14, v15
	v_cvt_pk_bf16_f32 v57, v16, v17
	v_mfma_f32_32x32x16_bf16 v[18:33], v[98:101], v[50:53], 0
	v_mfma_f32_32x32x16_bf16 v[34:49], v[106:109], v[50:53], 0
	s_add_u32 s14, s14, 0x8000
	s_addc_u32 s15, s15, 0
	v_mfma_f32_32x32x16_bf16 v[18:33], v[102:105], v[54:57], v[18:33]
	v_mfma_f32_32x32x16_bf16 v[34:49], v[110:113], v[54:57], v[34:49]
	v_mul_f32_e32 v2, v190, v2
	v_mul_f32_e32 v3, v190, v3
	v_mul_f32_e32 v4, v190, v4
	v_mul_f32_e32 v5, v190, v5
	v_mul_f32_e32 v6, v190, v6
	v_mul_f32_e32 v7, v190, v7
	v_mul_f32_e32 v8, v190, v8
	v_mul_f32_e32 v9, v190, v9
	v_mul_f32_e32 v10, v190, v10
	v_mul_f32_e32 v11, v190, v11
	v_mul_f32_e32 v12, v190, v12
	v_mul_f32_e32 v13, v190, v13
	v_mul_f32_e32 v14, v190, v14
	v_mul_f32_e32 v15, v190, v15
	v_mul_f32_e32 v16, v190, v16
	v_mul_f32_e32 v17, v190, v17
	s_waitcnt lgkmcnt(0)
	s_cmp_eq_u32 s7, 0
	s_cbranch_scc0 .Lp2b_in_28
	v_mfma_f32_32x32x16_bf16 v[18:33], v[114:117], v[166:169], v[18:33]
	s_branch .Lp2b_in_29

; __device__ __forceinline__ void scan_phase(const bf16* q, const bf16* kdT, const bf16* vT, const bf16* Pp, bf16* o, LAS unsigned char* lds, int bid, int G, int wave, int lane, int tid) {
;     ...
;         SCAN_STEP(0, 2, 0, 1, 60); SCAN_STEP(1, 0, 1, 0, 61); SCAN_STEP(2, 1, 0, 1, 62); SCAN_STEP(0, 2, 1, 0, 63);
.Lp2b_in_29:
	v_mfma_f32_32x32x16_bf16 v[2:17], v[118:121], v[150:153], v[2:17]
	v_mfma_f32_32x32x16_bf16 v[2:17], v[122:125], v[154:157], v[2:17]
	v_mfma_f32_32x32x16_bf16 v[2:17], v[126:129], v[158:161], v[2:17]
	v_mfma_f32_32x32x16_bf16 v[2:17], v[130:133], v[162:165], v[2:17]
	s_nop 7
	v_cvt_pk_bf16_f32 v18, v18, v19
	v_cvt_pk_bf16_f32 v19, v20, v21
	v_cvt_pk_bf16_f32 v20, v22, v23
	v_cvt_pk_bf16_f32 v21, v24, v25
	v_cvt_pk_bf16_f32 v22, v26, v27
	v_cvt_pk_bf16_f32 v23, v28, v29
	v_cvt_pk_bf16_f32 v24, v30, v31
	v_cvt_pk_bf16_f32 v25, v32, v33
	ds_write_b128 v192, v[18:21]
	ds_write_b128 v192, v[22:25] offset:1024
	v_cvt_pk_bf16_f32 v34, v34, v35
	v_cvt_pk_bf16_f32 v35, v36, v37
	v_cvt_pk_bf16_f32 v36, v38, v39
	v_cvt_pk_bf16_f32 v37, v40, v41
	v_cvt_pk_bf16_f32 v38, v42, v43
	v_cvt_pk_bf16_f32 v39, v44, v45
	v_cvt_pk_bf16_f32 v40, v46, v47
	v_cvt_pk_bf16_f32 v41, v48, v49
	ds_write_b128 v192, v[34:37] offset:2048
	ds_write_b128 v192, v[38:41] offset:3072
	s_waitcnt lgkmcnt(0)
	s_barrier
	ds_read2st64_b64 v[18:21], v193 offset0:0 offset1:8
	ds_read2st64_b64 v[22:25], v193 offset0:16 offset1:24
	ds_read2st64_b64 v[26:29], v193 offset0:32 offset1:40
	ds_read2st64_b64 v[30:33], v193 offset0:48 offset1:56
	ds_read_b128 v[150:153], v195 offset:4096
	ds_read_b128 v[154:157], v195 offset:5120
	ds_read_b128 v[158:161], v195 offset:6144
	ds_read_b128 v[162:165], v195 offset:7168
	ds_read_b128 v[166:169], v196 offset:4096
	s_waitcnt lgkmcnt(8)
	v_lshlrev_b32_e32 v178, 16, v18
	v_and_b32_e32 v179, 0xffff0000, v18
	v_lshlrev_b32_e32 v180, 16, v19
	v_and_b32_e32 v181, 0xffff0000, v19
	v_add_f32_e32 v174, 0, v178
	v_add_f32_e32 v175, 0, v179
	v_add_f32_e32 v176, 0, v180
	v_add_f32_e32 v177, 0, v181
	v_lshlrev_b32_e32 v178, 16, v20
	v_and_b32_e32 v179, 0xffff0000, v20
	v_lshlrev_b32_e32 v180, 16, v21
	v_and_b32_e32 v181, 0xffff0000, v21
	v_add_f32_e32 v174, v174, v178
	v_add_f32_e32 v175, v175, v179
	v_add_f32_e32 v176, v176, v180
	v_add_f32_e32 v177, v177, v181
	s_waitcnt lgkmcnt(7)
	v_lshlrev_b32_e32 v178, 16, v22
	v_and_b32_e32 v179, 0xffff0000, v22
	v_lshlrev_b32_e32 v180, 16, v23
	v_and_b32_e32 v181, 0xffff0000, v23
	v_add_f32_e32 v174, v174, v178
	v_add_f32_e32 v175, v175, v179
	v_add_f32_e32 v176, v176, v180
	v_add_f32_e32 v177, v177, v181
	v_lshlrev_b32_e32 v178, 16, v24
	v_and_b32_e32 v179, 0xffff0000, v24
	v_lshlrev_b32_e32 v180, 16, v25
	v_and_b32_e32 v181, 0xffff0000, v25
	v_add_f32_e32 v174, v174, v178
	v_add_f32_e32 v175, v175, v179
	v_add_f32_e32 v176, v176, v180
	v_add_f32_e32 v177, v177, v181
	s_waitcnt lgkmcnt(6)
	v_lshlrev_b32_e32 v178, 16, v26
	v_and_b32_e32 v179, 0xffff0000, v26
	v_lshlrev_b32_e32 v180, 16, v27
	v_and_b32_e32 v181, 0xffff0000, v27
	v_add_f32_e32 v174, v174, v178
	v_add_f32_e32 v175, v175, v179
	v_add_f32_e32 v176, v176, v180
	v_add_f32_e32 v177, v177, v181
	v_lshlrev_b32_e32 v178, 16, v28
	v_and_b32_e32 v179, 0xffff0000, v28
	v_lshlrev_b32_e32 v180, 16, v29
	v_and_b32_e32 v181, 0xffff0000, v29
	v_add_f32_e32 v174, v174, v178
	v_add_f32_e32 v175, v175, v179
	v_add_f32_e32 v176, v176, v180
	v_add_f32_e32 v177, v177, v181
	s_waitcnt lgkmcnt(5)
	v_lshlrev_b32_e32 v178, 16, v30
	v_and_b32_e32 v179, 0xffff0000, v30
	v_lshlrev_b32_e32 v180, 16, v31
	v_and_b32_e32 v181, 0xffff0000, v31
	v_add_f32_e32 v174, v174, v178
	v_add_f32_e32 v175, v175, v179
	v_add_f32_e32 v176, v176, v180
	v_add_f32_e32 v177, v177, v181
	v_lshlrev_b32_e32 v178, 16, v32
	v_and_b32_e32 v179, 0xffff0000, v32
	v_lshlrev_b32_e32 v180, 16, v33
	v_and_b32_e32 v181, 0xffff0000, v33
	v_add_f32_e32 v174, v174, v178
	v_add_f32_e32 v175, v175, v179
	v_add_f32_e32 v176, v176, v180
	v_add_f32_e32 v177, v177, v181
	v_mul_f32_e32 v174, v186, v174
	v_mul_f32_e32 v175, v187, v175
	v_mul_f32_e32 v176, v188, v176
	v_mul_f32_e32 v177, v189, v177
	v_bfe_u32 v178, v174, 16, 1
	v_bfe_u32 v179, v175, 16, 1
	v_bfe_u32 v180, v176, 16, 1
	v_bfe_u32 v181, v177, 16, 1
	v_add3_u32 v174, v174, v178, s23
	v_add3_u32 v175, v175, v179, s23
	v_add3_u32 v176, v176, v180, s23
	v_add3_u32 v177, v177, v181, s23
	global_store_short_d16_hi v197, v174, s[20:21] offset:-4096
	global_store_short_d16_hi v197, v175, s[20:21]
	global_store_short_d16_hi v198, v176, s[20:21] offset:-4096
	global_store_short_d16_hi v198, v177, s[20:21]
	s_add_u32 s20, s20, 0x40000
	s_addc_u32 s21, s21, 0
	s_waitcnt vmcnt(4)
	v_cvt_pk_bf16_f32 v50, v2, v3
	v_cvt_pk_bf16_f32 v51, v4, v5
	v_cvt_pk_bf16_f32 v52, v6, v7
	v_cvt_pk_bf16_f32 v53, v8, v9
	v_cvt_pk_bf16_f32 v54, v10, v11
	v_cvt_pk_bf16_f32 v55, v12, v13
	v_cvt_pk_bf16_f32 v56, v14, v15
	v_cvt_pk_bf16_f32 v57, v16, v17
	v_mfma_f32_32x32x16_bf16 v[18:33], v[58:61], v[50:53], 0
	v_mfma_f32_32x32x16_bf16 v[34:49], v[66:69], v[50:53], 0
	v_mfma_f32_32x32x16_bf16 v[18:33], v[62:65], v[54:57], v[18:33]
	v_mfma_f32_32x32x16_bf16 v[34:49], v[70:73], v[54:57], v[34:49]
	v_mul_f32_e32 v2, v190, v2
	v_mul_f32_e32 v3, v190, v3
	v_mul_f32_e32 v4, v190, v4
	v_mul_f32_e32 v5, v190, v5
	v_mul_f32_e32 v6, v190, v6
	v_mul_f32_e32 v7, v190, v7
	v_mul_f32_e32 v8, v190, v8
	v_mul_f32_e32 v9, v190, v9
	v_mul_f32_e32 v10, v190, v10
	v_mul_f32_e32 v11, v190, v11
	v_mul_f32_e32 v12, v190, v12
	v_mul_f32_e32 v13, v190, v13
	v_mul_f32_e32 v14, v190, v14
	v_mul_f32_e32 v15, v190, v15
	v_mul_f32_e32 v16, v190, v16
	v_mul_f32_e32 v17, v190, v17
	s_waitcnt lgkmcnt(0)
	s_cmp_eq_u32 s7, 0
	s_cbranch_scc0 .Lp2b_in_30
	v_mfma_f32_32x32x16_bf16 v[18:33], v[74:77], v[166:169], v[18:33]
	s_branch .Lp2b_in_31

; __device__ __forceinline__ void scan_phase(const bf16* q, const bf16* kdT, const bf16* vT, const bf16* Pp, bf16* o, LAS unsigned char* lds, int bid, int G, int wave, int lane, int tid) {
;     ...
;         SCAN_STEP(0, 2, 0, 1, 60); SCAN_STEP(1, 0, 1, 0, 61); SCAN_STEP(2, 1, 0, 1, 62); SCAN_STEP(0, 2, 1, 0, 63);
;     ...
;         __syncthreads();
.Lp2b_in_31:
	v_mfma_f32_32x32x16_bf16 v[2:17], v[134:137], v[150:153], v[2:17]
	v_mfma_f32_32x32x16_bf16 v[2:17], v[138:141], v[154:157], v[2:17]
	v_mfma_f32_32x32x16_bf16 v[2:17], v[142:145], v[158:161], v[2:17]
	v_mfma_f32_32x32x16_bf16 v[2:17], v[146:149], v[162:165], v[2:17]
	s_nop 7
	v_cvt_pk_bf16_f32 v18, v18, v19
	v_cvt_pk_bf16_f32 v19, v20, v21
	v_cvt_pk_bf16_f32 v20, v22, v23
	v_cvt_pk_bf16_f32 v21, v24, v25
	v_cvt_pk_bf16_f32 v22, v26, v27
	v_cvt_pk_bf16_f32 v23, v28, v29
	v_cvt_pk_bf16_f32 v24, v30, v31
	v_cvt_pk_bf16_f32 v25, v32, v33
	ds_write_b128 v192, v[18:21] offset:32768
	ds_write_b128 v192, v[22:25] offset:33792
	v_cvt_pk_bf16_f32 v34, v34, v35
	v_cvt_pk_bf16_f32 v35, v36, v37
	v_cvt_pk_bf16_f32 v36, v38, v39
	v_cvt_pk_bf16_f32 v37, v40, v41
	v_cvt_pk_bf16_f32 v38, v42, v43
	v_cvt_pk_bf16_f32 v39, v44, v45
	v_cvt_pk_bf16_f32 v40, v46, v47
	v_cvt_pk_bf16_f32 v41, v48, v49
	ds_write_b128 v192, v[34:37] offset:34816
	ds_write_b128 v192, v[38:41] offset:35840
	s_waitcnt lgkmcnt(0)
	s_barrier
	ds_read2st64_b64 v[18:21], v193 offset0:64 offset1:72
	ds_read2st64_b64 v[22:25], v193 offset0:80 offset1:88
	ds_read2st64_b64 v[26:29], v193 offset0:96 offset1:104
	ds_read2st64_b64 v[30:33], v193 offset0:112 offset1:120
	s_waitcnt lgkmcnt(3)
	v_lshlrev_b32_e32 v178, 16, v18
	v_and_b32_e32 v179, 0xffff0000, v18
	v_lshlrev_b32_e32 v180, 16, v19
	v_and_b32_e32 v181, 0xffff0000, v19
	v_add_f32_e32 v174, 0, v178
	v_add_f32_e32 v175, 0, v179
	v_add_f32_e32 v176, 0, v180
	v_add_f32_e32 v177, 0, v181
	v_lshlrev_b32_e32 v178, 16, v20
	v_and_b32_e32 v179, 0xffff0000, v20
	v_lshlrev_b32_e32 v180, 16, v21
	v_and_b32_e32 v181, 0xffff0000, v21
	v_add_f32_e32 v174, v174, v178
	v_add_f32_e32 v175, v175, v179
	v_add_f32_e32 v176, v176, v180
	v_add_f32_e32 v177, v177, v181
	s_waitcnt lgkmcnt(2)
	v_lshlrev_b32_e32 v178, 16, v22
	v_and_b32_e32 v179, 0xffff0000, v22
	v_lshlrev_b32_e32 v180, 16, v23
	v_and_b32_e32 v181, 0xffff0000, v23
	v_add_f32_e32 v174, v174, v178
	v_add_f32_e32 v175, v175, v179
	v_add_f32_e32 v176, v176, v180
	v_add_f32_e32 v177, v177, v181
	v_lshlrev_b32_e32 v178, 16, v24
	v_and_b32_e32 v179, 0xffff0000, v24
	v_lshlrev_b32_e32 v180, 16, v25
	v_and_b32_e32 v181, 0xffff0000, v25
	v_add_f32_e32 v174, v174, v178
	v_add_f32_e32 v175, v175, v179
	v_add_f32_e32 v176, v176, v180
	v_add_f32_e32 v177, v177, v181
	s_waitcnt lgkmcnt(1)
	v_lshlrev_b32_e32 v178, 16, v26
	v_and_b32_e32 v179, 0xffff0000, v26
	v_lshlrev_b32_e32 v180, 16, v27
	v_and_b32_e32 v181, 0xffff0000, v27
	v_add_f32_e32 v174, v174, v178
	v_add_f32_e32 v175, v175, v179
	v_add_f32_e32 v176, v176, v180
	v_add_f32_e32 v177, v177, v181
	v_lshlrev_b32_e32 v178, 16, v28
	v_and_b32_e32 v179, 0xffff0000, v28
	v_lshlrev_b32_e32 v180, 16, v29
	v_and_b32_e32 v181, 0xffff0000, v29
	v_add_f32_e32 v174, v174, v178
	v_add_f32_e32 v175, v175, v179
	v_add_f32_e32 v176, v176, v180
	v_add_f32_e32 v177, v177, v181
	s_waitcnt lgkmcnt(0)
	v_lshlrev_b32_e32 v178, 16, v30
	v_and_b32_e32 v179, 0xffff0000, v30
	v_lshlrev_b32_e32 v180, 16, v31
	v_and_b32_e32 v181, 0xffff0000, v31
	v_add_f32_e32 v174, v174, v178
	v_add_f32_e32 v175, v175, v179
	v_add_f32_e32 v176, v176, v180
	v_add_f32_e32 v177, v177, v181
	v_lshlrev_b32_e32 v178, 16, v32
	v_and_b32_e32 v179, 0xffff0000, v32
	v_lshlrev_b32_e32 v180, 16, v33
	v_and_b32_e32 v181, 0xffff0000, v33
	v_add_f32_e32 v174, v174, v178
	v_add_f32_e32 v175, v175, v179
	v_add_f32_e32 v176, v176, v180
	v_add_f32_e32 v177, v177, v181
	v_mul_f32_e32 v174, v186, v174
	v_mul_f32_e32 v175, v187, v175
	v_mul_f32_e32 v176, v188, v176
	v_mul_f32_e32 v177, v189, v177
	v_bfe_u32 v178, v174, 16, 1
	v_bfe_u32 v179, v175, 16, 1
	v_bfe_u32 v180, v176, 16, 1
	v_bfe_u32 v181, v177, 16, 1
	v_add3_u32 v174, v174, v178, s23
	v_add3_u32 v175, v175, v179, s23
	v_add3_u32 v176, v176, v180, s23
	v_add3_u32 v177, v177, v181, s23
	global_store_short_d16_hi v197, v174, s[20:21] offset:-4096
	global_store_short_d16_hi v197, v175, s[20:21]
	global_store_short_d16_hi v198, v176, s[20:21] offset:-4096
	global_store_short_d16_hi v198, v177, s[20:21]
	s_add_u32 s20, s20, 0x40000
	s_addc_u32 s21, s21, 0
	s_barrier
